# top-k bit search starts at bit 27 (13 values >= 2^28 is impossible: importance mass <= 4 heads * 2 * 2^28), plus the 1-row / 2-row specialisations
# baseline (speedup 1.0000x reference)
; __device__ __forceinline__ void phase_cmp(const Params& p, LAS unsigned char* lds, const bf16_t* Z, const float* G, const bf16_t* KC, const bf16_t* ACCW, float* ACC, int* IDX, ...
;     ...
;             for (int qi = wid; qi < 64; qi += 8) {
;                 const int cur = qb;
;                 unsigned v[4]; bool ok[4];
; #pragma unroll
;                 for (int i = 0; i < 4; ++i) { const int j = lane + 64 * i; ok[i] = (j >= 1) && (j <= cur - 2); v[i] = ok[i] ? PS[j * 64 + qi] : 0u; }
;                 unsigned T = 0u;
;     ...
; #pragma unroll
;                     for (int i = 0; i < 4; ++i) cnt += __builtin_popcountll(__ballot(ok[i] && v[i] >= trial));
;                     if (cnt >= 13) T = trial; }
.LBB0_433:
	s_waitcnt lgkmcnt(0)
	s_cmp_lt_u32 s91, 66
	s_cbranch_scc1 .Ltk_r1
	s_cmpk_lt_u32 s91, 0x82
	s_cbranch_scc1 .Ltk_r2
	s_or_b32 s23, s96, 0x8000000
	v_cmp_le_u32_e64 s[20:21], s23, v2
	v_cmp_le_u32_e64 s[98:99], s23, v5
	v_cmp_le_u32_e64 s[100:101], s23, v4
	s_bcnt1_i32_b64 s24, s[20:21]
	v_cmp_le_u32_e64 s[20:21], s23, v0
	s_bcnt1_i32_b64 s25, s[98:99]
	s_add_i32 s24, s24, s25
	s_bcnt1_i32_b64 s25, s[100:101]
	s_add_i32 s24, s24, s25
	s_bcnt1_i32_b64 s25, s[20:21]
	s_add_i32 s24, s24, s25
	s_cmp_gt_u32 s24, 12
	s_cselect_b32 s96, s23, s96
	s_or_b32 s23, s96, 0x4000000
	v_cmp_le_u32_e64 s[20:21], s23, v2
	v_cmp_le_u32_e64 s[98:99], s23, v5
	v_cmp_le_u32_e64 s[100:101], s23, v4
	s_bcnt1_i32_b64 s24, s[20:21]
	v_cmp_le_u32_e64 s[20:21], s23, v0
	s_bcnt1_i32_b64 s25, s[98:99]
	s_add_i32 s24, s24, s25
	s_bcnt1_i32_b64 s25, s[100:101]
	s_add_i32 s24, s24, s25
	s_bcnt1_i32_b64 s25, s[20:21]
	s_add_i32 s24, s24, s25
	s_cmp_gt_u32 s24, 12
	s_cselect_b32 s96, s23, s96
	s_or_b32 s23, s96, 0x2000000
	v_cmp_le_u32_e64 s[20:21], s23, v2
	v_cmp_le_u32_e64 s[98:99], s23, v5
	v_cmp_le_u32_e64 s[100:101], s23, v4
	s_bcnt1_i32_b64 s24, s[20:21]
	v_cmp_le_u32_e64 s[20:21], s23, v0
	s_bcnt1_i32_b64 s25, s[98:99]
	s_add_i32 s24, s24, s25
	s_bcnt1_i32_b64 s25, s[100:101]
	s_add_i32 s24, s24, s25
	s_bcnt1_i32_b64 s25, s[20:21]
	s_add_i32 s24, s24, s25
	s_cmp_gt_u32 s24, 12
	s_cselect_b32 s96, s23, s96
	s_or_b32 s23, s96, 0x1000000
	v_cmp_le_u32_e64 s[20:21], s23, v2
	v_cmp_le_u32_e64 s[98:99], s23, v5
	v_cmp_le_u32_e64 s[100:101], s23, v4
	s_bcnt1_i32_b64 s24, s[20:21]
	v_cmp_le_u32_e64 s[20:21], s23, v0
	s_bcnt1_i32_b64 s25, s[98:99]
	s_add_i32 s24, s24, s25
	s_bcnt1_i32_b64 s25, s[100:101]
	s_add_i32 s24, s24, s25
	s_bcnt1_i32_b64 s25, s[20:21]
	s_add_i32 s24, s24, s25
	s_cmp_gt_u32 s24, 12
	s_cselect_b32 s96, s23, s96
	s_or_b32 s23, s96, 0x800000
	v_cmp_le_u32_e64 s[20:21], s23, v2
	v_cmp_le_u32_e64 s[98:99], s23, v5
	v_cmp_le_u32_e64 s[100:101], s23, v4
	s_bcnt1_i32_b64 s24, s[20:21]
	v_cmp_le_u32_e64 s[20:21], s23, v0
	s_bcnt1_i32_b64 s25, s[98:99]
	s_add_i32 s24, s24, s25
	s_bcnt1_i32_b64 s25, s[100:101]
	s_add_i32 s24, s24, s25
	s_bcnt1_i32_b64 s25, s[20:21]
	s_add_i32 s24, s24, s25
	s_cmp_gt_u32 s24, 12
	s_cselect_b32 s96, s23, s96
	s_or_b32 s23, s96, 0x400000
	v_cmp_le_u32_e64 s[20:21], s23, v2
	v_cmp_le_u32_e64 s[98:99], s23, v5
	v_cmp_le_u32_e64 s[100:101], s23, v4
	s_bcnt1_i32_b64 s24, s[20:21]
	v_cmp_le_u32_e64 s[20:21], s23, v0
	s_bcnt1_i32_b64 s25, s[98:99]
	s_add_i32 s24, s24, s25
	s_bcnt1_i32_b64 s25, s[100:101]
	s_add_i32 s24, s24, s25
	s_bcnt1_i32_b64 s25, s[20:21]
	s_add_i32 s24, s24, s25
	s_cmp_gt_u32 s24, 12
	s_cselect_b32 s96, s23, s96
	s_or_b32 s23, s96, 0x200000
	v_cmp_le_u32_e64 s[20:21], s23, v2
	v_cmp_le_u32_e64 s[98:99], s23, v5
	v_cmp_le_u32_e64 s[100:101], s23, v4
	s_bcnt1_i32_b64 s24, s[20:21]
	v_cmp_le_u32_e64 s[20:21], s23, v0
	s_bcnt1_i32_b64 s25, s[98:99]
	s_add_i32 s24, s24, s25
	s_bcnt1_i32_b64 s25, s[100:101]
	s_add_i32 s24, s24, s25
	s_bcnt1_i32_b64 s25, s[20:21]
	s_add_i32 s24, s24, s25
	s_cmp_gt_u32 s24, 12
	s_cselect_b32 s96, s23, s96
	s_or_b32 s23, s96, 0x100000
	v_cmp_le_u32_e64 s[20:21], s23, v2
	v_cmp_le_u32_e64 s[98:99], s23, v5
	v_cmp_le_u32_e64 s[100:101], s23, v4
	s_bcnt1_i32_b64 s24, s[20:21]
	v_cmp_le_u32_e64 s[20:21], s23, v0
	s_bcnt1_i32_b64 s25, s[98:99]
	s_add_i32 s24, s24, s25
	s_bcnt1_i32_b64 s25, s[100:101]
	s_add_i32 s24, s24, s25
	s_bcnt1_i32_b64 s25, s[20:21]
	s_add_i32 s24, s24, s25
	s_cmp_gt_u32 s24, 12
	s_cselect_b32 s96, s23, s96
	s_or_b32 s23, s96, 0x80000
	v_cmp_le_u32_e64 s[20:21], s23, v2
	v_cmp_le_u32_e64 s[98:99], s23, v5
	v_cmp_le_u32_e64 s[100:101], s23, v4
	s_bcnt1_i32_b64 s24, s[20:21]
	v_cmp_le_u32_e64 s[20:21], s23, v0
	s_bcnt1_i32_b64 s25, s[98:99]
	s_add_i32 s24, s24, s25
	s_bcnt1_i32_b64 s25, s[100:101]
	s_add_i32 s24, s24, s25
	s_bcnt1_i32_b64 s25, s[20:21]
	s_add_i32 s24, s24, s25
	s_cmp_gt_u32 s24, 12
	s_cselect_b32 s96, s23, s96
	s_or_b32 s23, s96, 0x40000
	v_cmp_le_u32_e64 s[20:21], s23, v2
	v_cmp_le_u32_e64 s[98:99], s23, v5
	v_cmp_le_u32_e64 s[100:101], s23, v4
	s_bcnt1_i32_b64 s24, s[20:21]
	v_cmp_le_u32_e64 s[20:21], s23, v0
	s_bcnt1_i32_b64 s25, s[98:99]
	s_add_i32 s24, s24, s25
	s_bcnt1_i32_b64 s25, s[100:101]
	s_add_i32 s24, s24, s25
	s_bcnt1_i32_b64 s25, s[20:21]
	s_add_i32 s24, s24, s25
	s_cmp_gt_u32 s24, 12
	s_cselect_b32 s96, s23, s96
	s_or_b32 s23, s96, 0x20000
	v_cmp_le_u32_e64 s[20:21], s23, v2
	v_cmp_le_u32_e64 s[98:99], s23, v5
	v_cmp_le_u32_e64 s[100:101], s23, v4
	s_bcnt1_i32_b64 s24, s[20:21]
	v_cmp_le_u32_e64 s[20:21], s23, v0
	s_bcnt1_i32_b64 s25, s[98:99]
	s_add_i32 s24, s24, s25
	s_bcnt1_i32_b64 s25, s[100:101]
	s_add_i32 s24, s24, s25
	s_bcnt1_i32_b64 s25, s[20:21]
	s_add_i32 s24, s24, s25
	s_cmp_gt_u32 s24, 12
	s_cselect_b32 s96, s23, s96
	s_or_b32 s23, s96, 0x10000
	v_cmp_le_u32_e64 s[20:21], s23, v2
	v_cmp_le_u32_e64 s[98:99], s23, v5
	v_cmp_le_u32_e64 s[100:101], s23, v4
	s_bcnt1_i32_b64 s24, s[20:21]
	v_cmp_le_u32_e64 s[20:21], s23, v0
	s_bcnt1_i32_b64 s25, s[98:99]
	s_add_i32 s24, s24, s25
	s_bcnt1_i32_b64 s25, s[100:101]
	s_add_i32 s24, s24, s25
	s_bcnt1_i32_b64 s25, s[20:21]
	s_add_i32 s24, s24, s25
	s_cmp_gt_u32 s24, 12
	s_cselect_b32 s96, s23, s96
	s_or_b32 s23, s96, 0x8000
	v_cmp_le_u32_e64 s[20:21], s23, v2
	v_cmp_le_u32_e64 s[98:99], s23, v5
	v_cmp_le_u32_e64 s[100:101], s23, v4
	s_bcnt1_i32_b64 s24, s[20:21]
	v_cmp_le_u32_e64 s[20:21], s23, v0
	s_bcnt1_i32_b64 s25, s[98:99]
	s_add_i32 s24, s24, s25
	s_bcnt1_i32_b64 s25, s[100:101]
	s_add_i32 s24, s24, s25
	s_bcnt1_i32_b64 s25, s[20:21]
	s_add_i32 s24, s24, s25
	s_cmp_gt_u32 s24, 12
; __device__ __forceinline__ void phase_cmp(const Params& p, LAS unsigned char* lds, const bf16_t* Z, const float* G, const bf16_t* KC, const bf16_t* ACCW, float* ACC, int* IDX, ...
;     ...
; #pragma unroll
;                     for (int i = 0; i < 4; ++i) cnt += __builtin_popcountll(__ballot(ok[i] && v[i] >= trial));
;                     if (cnt >= 13) T = trial; }
	s_cselect_b32 s96, s23, s96
	s_or_b32 s23, s96, 0x4000
	v_cmp_le_u32_e64 s[20:21], s23, v2
	v_cmp_le_u32_e64 s[98:99], s23, v5
	v_cmp_le_u32_e64 s[100:101], s23, v4
	s_bcnt1_i32_b64 s24, s[20:21]
	v_cmp_le_u32_e64 s[20:21], s23, v0
	s_bcnt1_i32_b64 s25, s[98:99]
	s_add_i32 s24, s24, s25
	s_bcnt1_i32_b64 s25, s[100:101]
	s_add_i32 s24, s24, s25
	s_bcnt1_i32_b64 s25, s[20:21]
	s_add_i32 s24, s24, s25
	s_cmp_gt_u32 s24, 12
	s_cselect_b32 s96, s23, s96
	s_or_b32 s23, s96, 0x2000
	v_cmp_le_u32_e64 s[20:21], s23, v2
	v_cmp_le_u32_e64 s[98:99], s23, v5
	v_cmp_le_u32_e64 s[100:101], s23, v4
	s_bcnt1_i32_b64 s24, s[20:21]
	v_cmp_le_u32_e64 s[20:21], s23, v0
	s_bcnt1_i32_b64 s25, s[98:99]
	s_add_i32 s24, s24, s25
	s_bcnt1_i32_b64 s25, s[100:101]
	s_add_i32 s24, s24, s25
	s_bcnt1_i32_b64 s25, s[20:21]
	s_add_i32 s24, s24, s25
	s_cmp_gt_u32 s24, 12
	s_cselect_b32 s96, s23, s96
	s_or_b32 s23, s96, 0x1000
	v_cmp_le_u32_e64 s[20:21], s23, v2
	v_cmp_le_u32_e64 s[98:99], s23, v5
	v_cmp_le_u32_e64 s[100:101], s23, v4
	s_bcnt1_i32_b64 s24, s[20:21]
	v_cmp_le_u32_e64 s[20:21], s23, v0
	s_bcnt1_i32_b64 s25, s[98:99]
	s_add_i32 s24, s24, s25
	s_bcnt1_i32_b64 s25, s[100:101]
	s_add_i32 s24, s24, s25
	s_bcnt1_i32_b64 s25, s[20:21]
	s_add_i32 s24, s24, s25
	s_cmp_gt_u32 s24, 12
	s_cselect_b32 s96, s23, s96
	s_or_b32 s23, s96, 0x800
	v_cmp_le_u32_e64 s[20:21], s23, v2
	v_cmp_le_u32_e64 s[98:99], s23, v5
	v_cmp_le_u32_e64 s[100:101], s23, v4
	s_bcnt1_i32_b64 s24, s[20:21]
	v_cmp_le_u32_e64 s[20:21], s23, v0
	s_bcnt1_i32_b64 s25, s[98:99]
	s_add_i32 s24, s24, s25
	s_bcnt1_i32_b64 s25, s[100:101]
	s_add_i32 s24, s24, s25
	s_bcnt1_i32_b64 s25, s[20:21]
	s_add_i32 s24, s24, s25
	s_cmp_gt_u32 s24, 12
	s_cselect_b32 s96, s23, s96
	s_or_b32 s23, s96, 0x400
	v_cmp_le_u32_e64 s[20:21], s23, v2
	v_cmp_le_u32_e64 s[98:99], s23, v5
	v_cmp_le_u32_e64 s[100:101], s23, v4
	s_bcnt1_i32_b64 s24, s[20:21]
	v_cmp_le_u32_e64 s[20:21], s23, v0
	s_bcnt1_i32_b64 s25, s[98:99]
	s_add_i32 s24, s24, s25
	s_bcnt1_i32_b64 s25, s[100:101]
	s_add_i32 s24, s24, s25
	s_bcnt1_i32_b64 s25, s[20:21]
	s_add_i32 s24, s24, s25
	s_cmp_gt_u32 s24, 12
	s_cselect_b32 s96, s23, s96
	s_or_b32 s23, s96, 0x200
	v_cmp_le_u32_e64 s[20:21], s23, v2
	v_cmp_le_u32_e64 s[98:99], s23, v5
	v_cmp_le_u32_e64 s[100:101], s23, v4
	s_bcnt1_i32_b64 s24, s[20:21]
	v_cmp_le_u32_e64 s[20:21], s23, v0
	s_bcnt1_i32_b64 s25, s[98:99]
	s_add_i32 s24, s24, s25
	s_bcnt1_i32_b64 s25, s[100:101]
	s_add_i32 s24, s24, s25
	s_bcnt1_i32_b64 s25, s[20:21]
	s_add_i32 s24, s24, s25
	s_cmp_gt_u32 s24, 12
	s_cselect_b32 s96, s23, s96
	s_or_b32 s23, s96, 0x100
	v_cmp_le_u32_e64 s[20:21], s23, v2
	v_cmp_le_u32_e64 s[98:99], s23, v5
	v_cmp_le_u32_e64 s[100:101], s23, v4
	s_bcnt1_i32_b64 s24, s[20:21]
	v_cmp_le_u32_e64 s[20:21], s23, v0
	s_bcnt1_i32_b64 s25, s[98:99]
	s_add_i32 s24, s24, s25
	s_bcnt1_i32_b64 s25, s[100:101]
	s_add_i32 s24, s24, s25
	s_bcnt1_i32_b64 s25, s[20:21]
	s_add_i32 s24, s24, s25
	s_cmp_gt_u32 s24, 12
	s_cselect_b32 s96, s23, s96
	s_or_b32 s23, s96, 0x80
	v_cmp_le_u32_e64 s[20:21], s23, v2
	v_cmp_le_u32_e64 s[98:99], s23, v5
	v_cmp_le_u32_e64 s[100:101], s23, v4
	s_bcnt1_i32_b64 s24, s[20:21]
	v_cmp_le_u32_e64 s[20:21], s23, v0
	s_bcnt1_i32_b64 s25, s[98:99]
	s_add_i32 s24, s24, s25
	s_bcnt1_i32_b64 s25, s[100:101]
	s_add_i32 s24, s24, s25
	s_bcnt1_i32_b64 s25, s[20:21]
	s_add_i32 s24, s24, s25
	s_cmp_gt_u32 s24, 12
	s_cselect_b32 s96, s23, s96
	s_or_b32 s23, s96, 64
	v_cmp_le_u32_e64 s[20:21], s23, v2
	v_cmp_le_u32_e64 s[98:99], s23, v5
	v_cmp_le_u32_e64 s[100:101], s23, v4
	s_bcnt1_i32_b64 s24, s[20:21]
	v_cmp_le_u32_e64 s[20:21], s23, v0
	s_bcnt1_i32_b64 s25, s[98:99]
	s_add_i32 s24, s24, s25
	s_bcnt1_i32_b64 s25, s[100:101]
	s_add_i32 s24, s24, s25
	s_bcnt1_i32_b64 s25, s[20:21]
	s_add_i32 s24, s24, s25
	s_cmp_gt_u32 s24, 12
	s_cselect_b32 s96, s23, s96
	s_or_b32 s23, s96, 32
	v_cmp_le_u32_e64 s[20:21], s23, v2
	v_cmp_le_u32_e64 s[98:99], s23, v5
	v_cmp_le_u32_e64 s[100:101], s23, v4
	s_bcnt1_i32_b64 s24, s[20:21]
	v_cmp_le_u32_e64 s[20:21], s23, v0
	s_bcnt1_i32_b64 s25, s[98:99]
	s_add_i32 s24, s24, s25
	s_bcnt1_i32_b64 s25, s[100:101]
	s_add_i32 s24, s24, s25
	s_bcnt1_i32_b64 s25, s[20:21]
	s_add_i32 s24, s24, s25
	s_cmp_gt_u32 s24, 12
	s_cselect_b32 s96, s23, s96
	s_or_b32 s23, s96, 16
	v_cmp_le_u32_e64 s[20:21], s23, v2
	v_cmp_le_u32_e64 s[98:99], s23, v5
	v_cmp_le_u32_e64 s[100:101], s23, v4
	s_bcnt1_i32_b64 s24, s[20:21]
	v_cmp_le_u32_e64 s[20:21], s23, v0
	s_bcnt1_i32_b64 s25, s[98:99]
	s_add_i32 s24, s24, s25
	s_bcnt1_i32_b64 s25, s[100:101]
	s_add_i32 s24, s24, s25
	s_bcnt1_i32_b64 s25, s[20:21]
	s_add_i32 s24, s24, s25
	s_cmp_gt_u32 s24, 12
	s_cselect_b32 s96, s23, s96
	s_or_b32 s23, s96, 8
	v_cmp_le_u32_e64 s[20:21], s23, v2
	v_cmp_le_u32_e64 s[98:99], s23, v5
	v_cmp_le_u32_e64 s[100:101], s23, v4
	s_bcnt1_i32_b64 s24, s[20:21]
	v_cmp_le_u32_e64 s[20:21], s23, v0
	s_bcnt1_i32_b64 s25, s[98:99]
	s_add_i32 s24, s24, s25
	s_bcnt1_i32_b64 s25, s[100:101]
	s_add_i32 s24, s24, s25
	s_bcnt1_i32_b64 s25, s[20:21]
	s_add_i32 s24, s24, s25
	s_cmp_gt_u32 s24, 12
	s_cselect_b32 s96, s23, s96
	s_or_b32 s23, s96, 4
	v_cmp_le_u32_e64 s[20:21], s23, v2
	v_cmp_le_u32_e64 s[98:99], s23, v5
	v_cmp_le_u32_e64 s[100:101], s23, v4
	s_bcnt1_i32_b64 s24, s[20:21]
	v_cmp_le_u32_e64 s[20:21], s23, v0
	s_bcnt1_i32_b64 s25, s[98:99]
	s_add_i32 s24, s24, s25
	s_bcnt1_i32_b64 s25, s[100:101]
	s_add_i32 s24, s24, s25
	s_bcnt1_i32_b64 s25, s[20:21]
	s_add_i32 s24, s24, s25
	s_cmp_gt_u32 s24, 12
	s_cselect_b32 s96, s23, s96
	s_or_b32 s23, s96, 2
	v_cmp_le_u32_e64 s[20:21], s23, v2
	v_cmp_le_u32_e64 s[98:99], s23, v5
	v_cmp_le_u32_e64 s[100:101], s23, v4
	s_bcnt1_i32_b64 s24, s[20:21]
	v_cmp_le_u32_e64 s[20:21], s23, v0
	s_bcnt1_i32_b64 s25, s[98:99]
	s_add_i32 s24, s24, s25
	s_bcnt1_i32_b64 s25, s[100:101]
	s_add_i32 s24, s24, s25
	s_bcnt1_i32_b64 s25, s[20:21]
	s_add_i32 s24, s24, s25
	s_cmp_gt_u32 s24, 12
	s_cselect_b32 s96, s23, s96
	s_or_b32 s23, s96, 1
	v_cmp_le_u32_e64 s[20:21], s23, v2
	v_cmp_le_u32_e64 s[98:99], s23, v5
	v_cmp_le_u32_e64 s[100:101], s23, v4
	s_bcnt1_i32_b64 s24, s[20:21]
	v_cmp_le_u32_e64 s[20:21], s23, v0
	s_bcnt1_i32_b64 s25, s[98:99]
	s_add_i32 s24, s24, s25
	s_bcnt1_i32_b64 s25, s[100:101]
	s_add_i32 s24, s24, s25
	s_bcnt1_i32_b64 s25, s[20:21]
	s_add_i32 s24, s24, s25
	s_cmp_gt_u32 s24, 12
	s_cselect_b32 s96, s23, s96
	s_branch .Ltk_join
; __device__ __forceinline__ void phase_cmp(const Params& p, LAS unsigned char* lds, const bf16_t* Z, const float* G, const bf16_t* KC, const bf16_t* ACCW, float* ACC, int* IDX, ...
;     ...
; #pragma unroll
;                     for (int i = 0; i < 4; ++i) cnt += __builtin_popcountll(__ballot(ok[i] && v[i] >= trial));
;                     if (cnt >= 13) T = trial; }
.Ltk_r1:
	s_or_b32 s23, s96, 0x8000000
	v_cmp_le_u32_e64 s[20:21], s23, v2
	s_bcnt1_i32_b64 s24, s[20:21]
	s_cmp_gt_u32 s24, 12
	s_cselect_b32 s96, s23, s96
	s_or_b32 s23, s96, 0x4000000
	v_cmp_le_u32_e64 s[20:21], s23, v2
	s_bcnt1_i32_b64 s24, s[20:21]
	s_cmp_gt_u32 s24, 12
	s_cselect_b32 s96, s23, s96
	s_or_b32 s23, s96, 0x2000000
	v_cmp_le_u32_e64 s[20:21], s23, v2
	s_bcnt1_i32_b64 s24, s[20:21]
	s_cmp_gt_u32 s24, 12
	s_cselect_b32 s96, s23, s96
	s_or_b32 s23, s96, 0x1000000
	v_cmp_le_u32_e64 s[20:21], s23, v2
	s_bcnt1_i32_b64 s24, s[20:21]
	s_cmp_gt_u32 s24, 12
	s_cselect_b32 s96, s23, s96
	s_or_b32 s23, s96, 0x800000
	v_cmp_le_u32_e64 s[20:21], s23, v2
	s_bcnt1_i32_b64 s24, s[20:21]
	s_cmp_gt_u32 s24, 12
	s_cselect_b32 s96, s23, s96
	s_or_b32 s23, s96, 0x400000
	v_cmp_le_u32_e64 s[20:21], s23, v2
	s_bcnt1_i32_b64 s24, s[20:21]
	s_cmp_gt_u32 s24, 12
	s_cselect_b32 s96, s23, s96
	s_or_b32 s23, s96, 0x200000
	v_cmp_le_u32_e64 s[20:21], s23, v2
	s_bcnt1_i32_b64 s24, s[20:21]
	s_cmp_gt_u32 s24, 12
	s_cselect_b32 s96, s23, s96
	s_or_b32 s23, s96, 0x100000
	v_cmp_le_u32_e64 s[20:21], s23, v2
	s_bcnt1_i32_b64 s24, s[20:21]
	s_cmp_gt_u32 s24, 12
	s_cselect_b32 s96, s23, s96
	s_or_b32 s23, s96, 0x80000
	v_cmp_le_u32_e64 s[20:21], s23, v2
	s_bcnt1_i32_b64 s24, s[20:21]
	s_cmp_gt_u32 s24, 12
	s_cselect_b32 s96, s23, s96
	s_or_b32 s23, s96, 0x40000
	v_cmp_le_u32_e64 s[20:21], s23, v2
	s_bcnt1_i32_b64 s24, s[20:21]
	s_cmp_gt_u32 s24, 12
	s_cselect_b32 s96, s23, s96
	s_or_b32 s23, s96, 0x20000
	v_cmp_le_u32_e64 s[20:21], s23, v2
	s_bcnt1_i32_b64 s24, s[20:21]
	s_cmp_gt_u32 s24, 12
	s_cselect_b32 s96, s23, s96
	s_or_b32 s23, s96, 0x10000
	v_cmp_le_u32_e64 s[20:21], s23, v2
	s_bcnt1_i32_b64 s24, s[20:21]
	s_cmp_gt_u32 s24, 12
	s_cselect_b32 s96, s23, s96
	s_or_b32 s23, s96, 0x8000
	v_cmp_le_u32_e64 s[20:21], s23, v2
	s_bcnt1_i32_b64 s24, s[20:21]
	s_cmp_gt_u32 s24, 12
	s_cselect_b32 s96, s23, s96
	s_or_b32 s23, s96, 0x4000
	v_cmp_le_u32_e64 s[20:21], s23, v2
	s_bcnt1_i32_b64 s24, s[20:21]
	s_cmp_gt_u32 s24, 12
	s_cselect_b32 s96, s23, s96
	s_or_b32 s23, s96, 0x2000
	v_cmp_le_u32_e64 s[20:21], s23, v2
	s_bcnt1_i32_b64 s24, s[20:21]
	s_cmp_gt_u32 s24, 12
	s_cselect_b32 s96, s23, s96
	s_or_b32 s23, s96, 0x1000
	v_cmp_le_u32_e64 s[20:21], s23, v2
	s_bcnt1_i32_b64 s24, s[20:21]
	s_cmp_gt_u32 s24, 12
	s_cselect_b32 s96, s23, s96
	s_or_b32 s23, s96, 0x800
	v_cmp_le_u32_e64 s[20:21], s23, v2
	s_bcnt1_i32_b64 s24, s[20:21]
	s_cmp_gt_u32 s24, 12
	s_cselect_b32 s96, s23, s96
	s_or_b32 s23, s96, 0x400
	v_cmp_le_u32_e64 s[20:21], s23, v2
	s_bcnt1_i32_b64 s24, s[20:21]
	s_cmp_gt_u32 s24, 12
	s_cselect_b32 s96, s23, s96
	s_or_b32 s23, s96, 0x200
	v_cmp_le_u32_e64 s[20:21], s23, v2
	s_bcnt1_i32_b64 s24, s[20:21]
	s_cmp_gt_u32 s24, 12
	s_cselect_b32 s96, s23, s96
	s_or_b32 s23, s96, 0x100
	v_cmp_le_u32_e64 s[20:21], s23, v2
	s_bcnt1_i32_b64 s24, s[20:21]
	s_cmp_gt_u32 s24, 12
	s_cselect_b32 s96, s23, s96
	s_or_b32 s23, s96, 0x80
	v_cmp_le_u32_e64 s[20:21], s23, v2
	s_bcnt1_i32_b64 s24, s[20:21]
	s_cmp_gt_u32 s24, 12
	s_cselect_b32 s96, s23, s96
	s_or_b32 s23, s96, 64
	v_cmp_le_u32_e64 s[20:21], s23, v2
	s_bcnt1_i32_b64 s24, s[20:21]
	s_cmp_gt_u32 s24, 12
	s_cselect_b32 s96, s23, s96
	s_or_b32 s23, s96, 32
	v_cmp_le_u32_e64 s[20:21], s23, v2
	s_bcnt1_i32_b64 s24, s[20:21]
	s_cmp_gt_u32 s24, 12
	s_cselect_b32 s96, s23, s96
	s_or_b32 s23, s96, 16
	v_cmp_le_u32_e64 s[20:21], s23, v2
	s_bcnt1_i32_b64 s24, s[20:21]
	s_cmp_gt_u32 s24, 12
	s_cselect_b32 s96, s23, s96
	s_or_b32 s23, s96, 8
	v_cmp_le_u32_e64 s[20:21], s23, v2
	s_bcnt1_i32_b64 s24, s[20:21]
	s_cmp_gt_u32 s24, 12
	s_cselect_b32 s96, s23, s96
	s_or_b32 s23, s96, 4
	v_cmp_le_u32_e64 s[20:21], s23, v2
	s_bcnt1_i32_b64 s24, s[20:21]
	s_cmp_gt_u32 s24, 12
	s_cselect_b32 s96, s23, s96
	s_or_b32 s23, s96, 2
	v_cmp_le_u32_e64 s[20:21], s23, v2
	s_bcnt1_i32_b64 s24, s[20:21]
	s_cmp_gt_u32 s24, 12
	s_cselect_b32 s96, s23, s96
	s_or_b32 s23, s96, 1
	v_cmp_le_u32_e64 s[20:21], s23, v2
	s_bcnt1_i32_b64 s24, s[20:21]
	s_cmp_gt_u32 s24, 12
	s_cselect_b32 s96, s23, s96
	s_branch .Ltk_join
; __device__ __forceinline__ void phase_cmp(const Params& p, LAS unsigned char* lds, const bf16_t* Z, const float* G, const bf16_t* KC, const bf16_t* ACCW, float* ACC, int* IDX, ...
;     ...
; #pragma unroll
;                     for (int i = 0; i < 4; ++i) cnt += __builtin_popcountll(__ballot(ok[i] && v[i] >= trial));
;                     if (cnt >= 13) T = trial; }
.Ltk_r2:
	s_or_b32 s23, s96, 0x8000000
	v_cmp_le_u32_e64 s[20:21], s23, v2
	v_cmp_le_u32_e64 s[98:99], s23, v5
	s_bcnt1_i32_b64 s24, s[20:21]
	s_bcnt1_i32_b64 s25, s[98:99]
	s_add_i32 s24, s24, s25
	s_cmp_gt_u32 s24, 12
	s_cselect_b32 s96, s23, s96
	s_or_b32 s23, s96, 0x4000000
	v_cmp_le_u32_e64 s[20:21], s23, v2
	v_cmp_le_u32_e64 s[98:99], s23, v5
	s_bcnt1_i32_b64 s24, s[20:21]
	s_bcnt1_i32_b64 s25, s[98:99]
	s_add_i32 s24, s24, s25
	s_cmp_gt_u32 s24, 12
	s_cselect_b32 s96, s23, s96
	s_or_b32 s23, s96, 0x2000000
	v_cmp_le_u32_e64 s[20:21], s23, v2
	v_cmp_le_u32_e64 s[98:99], s23, v5
	s_bcnt1_i32_b64 s24, s[20:21]
	s_bcnt1_i32_b64 s25, s[98:99]
	s_add_i32 s24, s24, s25
	s_cmp_gt_u32 s24, 12
	s_cselect_b32 s96, s23, s96
	s_or_b32 s23, s96, 0x1000000
	v_cmp_le_u32_e64 s[20:21], s23, v2
	v_cmp_le_u32_e64 s[98:99], s23, v5
	s_bcnt1_i32_b64 s24, s[20:21]
	s_bcnt1_i32_b64 s25, s[98:99]
	s_add_i32 s24, s24, s25
	s_cmp_gt_u32 s24, 12
	s_cselect_b32 s96, s23, s96
	s_or_b32 s23, s96, 0x800000
	v_cmp_le_u32_e64 s[20:21], s23, v2
	v_cmp_le_u32_e64 s[98:99], s23, v5
	s_bcnt1_i32_b64 s24, s[20:21]
	s_bcnt1_i32_b64 s25, s[98:99]
	s_add_i32 s24, s24, s25
	s_cmp_gt_u32 s24, 12
	s_cselect_b32 s96, s23, s96
	s_or_b32 s23, s96, 0x400000
	v_cmp_le_u32_e64 s[20:21], s23, v2
	v_cmp_le_u32_e64 s[98:99], s23, v5
	s_bcnt1_i32_b64 s24, s[20:21]
	s_bcnt1_i32_b64 s25, s[98:99]
	s_add_i32 s24, s24, s25
	s_cmp_gt_u32 s24, 12
	s_cselect_b32 s96, s23, s96
	s_or_b32 s23, s96, 0x200000
	v_cmp_le_u32_e64 s[20:21], s23, v2
	v_cmp_le_u32_e64 s[98:99], s23, v5
	s_bcnt1_i32_b64 s24, s[20:21]
	s_bcnt1_i32_b64 s25, s[98:99]
	s_add_i32 s24, s24, s25
	s_cmp_gt_u32 s24, 12
	s_cselect_b32 s96, s23, s96
	s_or_b32 s23, s96, 0x100000
	v_cmp_le_u32_e64 s[20:21], s23, v2
	v_cmp_le_u32_e64 s[98:99], s23, v5
	s_bcnt1_i32_b64 s24, s[20:21]
	s_bcnt1_i32_b64 s25, s[98:99]
	s_add_i32 s24, s24, s25
	s_cmp_gt_u32 s24, 12
	s_cselect_b32 s96, s23, s96
	s_or_b32 s23, s96, 0x80000
	v_cmp_le_u32_e64 s[20:21], s23, v2
	v_cmp_le_u32_e64 s[98:99], s23, v5
	s_bcnt1_i32_b64 s24, s[20:21]
	s_bcnt1_i32_b64 s25, s[98:99]
	s_add_i32 s24, s24, s25
	s_cmp_gt_u32 s24, 12
	s_cselect_b32 s96, s23, s96
	s_or_b32 s23, s96, 0x40000
	v_cmp_le_u32_e64 s[20:21], s23, v2
	v_cmp_le_u32_e64 s[98:99], s23, v5
	s_bcnt1_i32_b64 s24, s[20:21]
	s_bcnt1_i32_b64 s25, s[98:99]
	s_add_i32 s24, s24, s25
	s_cmp_gt_u32 s24, 12
	s_cselect_b32 s96, s23, s96
	s_or_b32 s23, s96, 0x20000
	v_cmp_le_u32_e64 s[20:21], s23, v2
	v_cmp_le_u32_e64 s[98:99], s23, v5
	s_bcnt1_i32_b64 s24, s[20:21]
	s_bcnt1_i32_b64 s25, s[98:99]
	s_add_i32 s24, s24, s25
	s_cmp_gt_u32 s24, 12
	s_cselect_b32 s96, s23, s96
	s_or_b32 s23, s96, 0x10000
	v_cmp_le_u32_e64 s[20:21], s23, v2
	v_cmp_le_u32_e64 s[98:99], s23, v5
	s_bcnt1_i32_b64 s24, s[20:21]
	s_bcnt1_i32_b64 s25, s[98:99]
	s_add_i32 s24, s24, s25
	s_cmp_gt_u32 s24, 12
	s_cselect_b32 s96, s23, s96
	s_or_b32 s23, s96, 0x8000
	v_cmp_le_u32_e64 s[20:21], s23, v2
	v_cmp_le_u32_e64 s[98:99], s23, v5
	s_bcnt1_i32_b64 s24, s[20:21]
	s_bcnt1_i32_b64 s25, s[98:99]
	s_add_i32 s24, s24, s25
	s_cmp_gt_u32 s24, 12
	s_cselect_b32 s96, s23, s96
	s_or_b32 s23, s96, 0x4000
	v_cmp_le_u32_e64 s[20:21], s23, v2
	v_cmp_le_u32_e64 s[98:99], s23, v5
	s_bcnt1_i32_b64 s24, s[20:21]
	s_bcnt1_i32_b64 s25, s[98:99]
	s_add_i32 s24, s24, s25
	s_cmp_gt_u32 s24, 12
	s_cselect_b32 s96, s23, s96
	s_or_b32 s23, s96, 0x2000
	v_cmp_le_u32_e64 s[20:21], s23, v2
	v_cmp_le_u32_e64 s[98:99], s23, v5
	s_bcnt1_i32_b64 s24, s[20:21]
	s_bcnt1_i32_b64 s25, s[98:99]
	s_add_i32 s24, s24, s25
	s_cmp_gt_u32 s24, 12
	s_cselect_b32 s96, s23, s96
	s_or_b32 s23, s96, 0x1000
	v_cmp_le_u32_e64 s[20:21], s23, v2
	v_cmp_le_u32_e64 s[98:99], s23, v5
	s_bcnt1_i32_b64 s24, s[20:21]
	s_bcnt1_i32_b64 s25, s[98:99]
	s_add_i32 s24, s24, s25
	s_cmp_gt_u32 s24, 12
	s_cselect_b32 s96, s23, s96
	s_or_b32 s23, s96, 0x800
	v_cmp_le_u32_e64 s[20:21], s23, v2
	v_cmp_le_u32_e64 s[98:99], s23, v5
	s_bcnt1_i32_b64 s24, s[20:21]
	s_bcnt1_i32_b64 s25, s[98:99]
	s_add_i32 s24, s24, s25
	s_cmp_gt_u32 s24, 12
	s_cselect_b32 s96, s23, s96
	s_or_b32 s23, s96, 0x400
	v_cmp_le_u32_e64 s[20:21], s23, v2
	v_cmp_le_u32_e64 s[98:99], s23, v5
	s_bcnt1_i32_b64 s24, s[20:21]
	s_bcnt1_i32_b64 s25, s[98:99]
	s_add_i32 s24, s24, s25
	s_cmp_gt_u32 s24, 12
	s_cselect_b32 s96, s23, s96
	s_or_b32 s23, s96, 0x200
	v_cmp_le_u32_e64 s[20:21], s23, v2
	v_cmp_le_u32_e64 s[98:99], s23, v5
	s_bcnt1_i32_b64 s24, s[20:21]
	s_bcnt1_i32_b64 s25, s[98:99]
	s_add_i32 s24, s24, s25
	s_cmp_gt_u32 s24, 12
	s_cselect_b32 s96, s23, s96
	s_or_b32 s23, s96, 0x100
	v_cmp_le_u32_e64 s[20:21], s23, v2
	v_cmp_le_u32_e64 s[98:99], s23, v5
	s_bcnt1_i32_b64 s24, s[20:21]
	s_bcnt1_i32_b64 s25, s[98:99]
	s_add_i32 s24, s24, s25
	s_cmp_gt_u32 s24, 12
	s_cselect_b32 s96, s23, s96
	s_or_b32 s23, s96, 0x80
	v_cmp_le_u32_e64 s[20:21], s23, v2
	v_cmp_le_u32_e64 s[98:99], s23, v5
	s_bcnt1_i32_b64 s24, s[20:21]
	s_bcnt1_i32_b64 s25, s[98:99]
	s_add_i32 s24, s24, s25
	s_cmp_gt_u32 s24, 12
	s_cselect_b32 s96, s23, s96
	s_or_b32 s23, s96, 64
	v_cmp_le_u32_e64 s[20:21], s23, v2
	v_cmp_le_u32_e64 s[98:99], s23, v5
	s_bcnt1_i32_b64 s24, s[20:21]
	s_bcnt1_i32_b64 s25, s[98:99]
	s_add_i32 s24, s24, s25
	s_cmp_gt_u32 s24, 12
	s_cselect_b32 s96, s23, s96
	s_or_b32 s23, s96, 32
	v_cmp_le_u32_e64 s[20:21], s23, v2
	v_cmp_le_u32_e64 s[98:99], s23, v5
	s_bcnt1_i32_b64 s24, s[20:21]
	s_bcnt1_i32_b64 s25, s[98:99]
	s_add_i32 s24, s24, s25
	s_cmp_gt_u32 s24, 12
	s_cselect_b32 s96, s23, s96
	s_or_b32 s23, s96, 16
	v_cmp_le_u32_e64 s[20:21], s23, v2
	v_cmp_le_u32_e64 s[98:99], s23, v5
	s_bcnt1_i32_b64 s24, s[20:21]
	s_bcnt1_i32_b64 s25, s[98:99]
	s_add_i32 s24, s24, s25
	s_cmp_gt_u32 s24, 12
	s_cselect_b32 s96, s23, s96
	s_or_b32 s23, s96, 8
	v_cmp_le_u32_e64 s[20:21], s23, v2
	v_cmp_le_u32_e64 s[98:99], s23, v5
	s_bcnt1_i32_b64 s24, s[20:21]
	s_bcnt1_i32_b64 s25, s[98:99]
	s_add_i32 s24, s24, s25
	s_cmp_gt_u32 s24, 12
	s_cselect_b32 s96, s23, s96
	s_or_b32 s23, s96, 4
	v_cmp_le_u32_e64 s[20:21], s23, v2
	v_cmp_le_u32_e64 s[98:99], s23, v5
	s_bcnt1_i32_b64 s24, s[20:21]
	s_bcnt1_i32_b64 s25, s[98:99]
	s_add_i32 s24, s24, s25
	s_cmp_gt_u32 s24, 12
	s_cselect_b32 s96, s23, s96
	s_or_b32 s23, s96, 2
	v_cmp_le_u32_e64 s[20:21], s23, v2
	v_cmp_le_u32_e64 s[98:99], s23, v5
	s_bcnt1_i32_b64 s24, s[20:21]
	s_bcnt1_i32_b64 s25, s[98:99]
	s_add_i32 s24, s24, s25
	s_cmp_gt_u32 s24, 12
	s_cselect_b32 s96, s23, s96
	s_or_b32 s23, s96, 1
	v_cmp_le_u32_e64 s[20:21], s23, v2
	v_cmp_le_u32_e64 s[98:99], s23, v5
	s_bcnt1_i32_b64 s24, s[20:21]
	s_bcnt1_i32_b64 s25, s[98:99]
	s_add_i32 s24, s24, s25
	s_cmp_gt_u32 s24, 12
	s_cselect_b32 s96, s23, s96
